# attention loop: cross-half shuffle address and V^T read bases hoisted out of the tile loop (on top of prefetch-offset hoist and in-place bias)
# baseline (speedup 1.0000x reference)
.LBB0_376:
	s_or_b64 exec, exec, s[40:41]
	v_or_b32_e32 v122, v122, v130
	v_lshlrev_b64 v[34:35], 1, v[122:123]
	v_or_b32_e32 v34, 0x400, v34
	v_lshl_add_u64 v[36:37], v[114:115], 0, v[34:35]
	global_load_dwordx2 v[38:39], v[36:37], off
	global_load_dwordx2 v[40:41], v[36:37], off offset:16
	global_load_dwordx2 v[42:43], v[36:37], off offset:32
	global_load_dwordx2 v[44:45], v[36:37], off offset:48
	global_load_dwordx2 v[46:47], v[36:37], off offset:64
	global_load_dwordx2 v[50:51], v[36:37], off offset:80
	ds_bpermute_b32 v33, v223, v32
	global_load_dwordx2 v[48:49], v[36:37], off offset:96
	v_lshl_add_u64 v[34:35], v[116:117], 0, v[34:35]
	s_waitcnt lgkmcnt(0)
	v_add_f32_e32 v52, v32, v33
	global_load_dwordx2 v[32:33], v[36:37], off offset:112
	v_div_scale_f32 v53, s[6:7], v52, v52, 1.0
	v_rcp_f32_e32 v54, v53
	v_div_scale_f32 v36, vcc, 1.0, v52, 1.0
	v_fma_f32 v37, -v53, v54, 1.0
	v_fmac_f32_e32 v54, v37, v54
	v_mul_f32_e32 v37, v36, v54
	v_fma_f32 v55, -v53, v37, v36
	v_fmac_f32_e32 v37, v55, v54
	v_fma_f32 v36, -v53, v37, v36
	v_div_fmas_f32 v36, v36, v54, v37
	v_div_fixup_f32 v36, v36, v52, 1.0
	v_pk_mul_f32 v[16:17], v[16:17], v[36:37] op_sel_hi:[1,0]
	v_pk_mul_f32 v[18:19], v[18:19], v[36:37] op_sel_hi:[1,0]
	v_pk_mul_f32 v[0:1], v[0:1], v[36:37] op_sel_hi:[1,0]
	v_pk_mul_f32 v[2:3], v[2:3], v[36:37] op_sel_hi:[1,0]
	v_pk_mul_f32 v[20:21], v[20:21], v[36:37] op_sel_hi:[1,0]
	v_pk_mul_f32 v[22:23], v[22:23], v[36:37] op_sel_hi:[1,0]
	v_pk_mul_f32 v[24:25], v[24:25], v[36:37] op_sel_hi:[1,0]
	v_pk_mul_f32 v[26:27], v[26:27], v[36:37] op_sel_hi:[1,0]
	v_pk_mul_f32 v[28:29], v[28:29], v[36:37] op_sel_hi:[1,0]
	v_pk_mul_f32 v[30:31], v[30:31], v[36:37] op_sel_hi:[1,0]
	v_pk_mul_f32 v[4:5], v[4:5], v[36:37] op_sel_hi:[1,0]
	s_waitcnt vmcnt(7)
	v_lshlrev_b32_e32 v52, 16, v38
	v_and_b32_e32 v53, 0xffff0000, v38
	v_lshlrev_b32_e32 v38, 16, v39
	v_and_b32_e32 v39, 0xffff0000, v39
	s_waitcnt vmcnt(3)
	v_lshlrev_b32_e32 v60, 16, v46
	v_and_b32_e32 v61, 0xffff0000, v46
	v_lshlrev_b32_e32 v46, 16, v47
	v_and_b32_e32 v47, 0xffff0000, v47
	v_lshlrev_b32_e32 v54, 16, v40
	v_and_b32_e32 v55, 0xffff0000, v40
	v_lshlrev_b32_e32 v40, 16, v41
	v_and_b32_e32 v41, 0xffff0000, v41
	v_lshlrev_b32_e32 v56, 16, v42
	v_and_b32_e32 v57, 0xffff0000, v42
	v_lshlrev_b32_e32 v42, 16, v43
	v_and_b32_e32 v43, 0xffff0000, v43
	v_lshlrev_b32_e32 v58, 16, v44
	v_and_b32_e32 v59, 0xffff0000, v44
	v_lshlrev_b32_e32 v44, 16, v45
	v_and_b32_e32 v45, 0xffff0000, v45
	v_pk_mul_f32 v[16:17], v[16:17], v[52:53]
	v_pk_mul_f32 v[18:19], v[18:19], v[38:39]
	v_pk_mul_f32 v[0:1], v[0:1], v[60:61]
	v_pk_mul_f32 v[2:3], v[2:3], v[46:47]
	v_pk_mul_f32 v[20:21], v[20:21], v[54:55]
	v_pk_mul_f32 v[22:23], v[22:23], v[40:41]
	v_pk_mul_f32 v[24:25], v[24:25], v[56:57]
	v_pk_mul_f32 v[26:27], v[26:27], v[42:43]
	v_pk_mul_f32 v[28:29], v[28:29], v[58:59]
	v_pk_mul_f32 v[30:31], v[30:31], v[44:45]
	v_cvt_pk_bf16_f32 v16, v16, v17
	v_cvt_pk_bf16_f32 v17, v18, v19
	v_cvt_pk_bf16_f32 v0, v0, v1
	v_cvt_pk_bf16_f32 v1, v2, v3
	s_waitcnt vmcnt(2)
	v_lshlrev_b32_e32 v62, 16, v50
	v_and_b32_e32 v63, 0xffff0000, v50
	v_cvt_pk_bf16_f32 v18, v20, v21
	v_cvt_pk_bf16_f32 v19, v22, v23
	v_cvt_pk_bf16_f32 v20, v24, v25
	v_cvt_pk_bf16_f32 v21, v26, v27
	v_cvt_pk_bf16_f32 v22, v28, v29
	v_cvt_pk_bf16_f32 v23, v30, v31
	global_store_dwordx2 v[34:35], v[16:17], off
	global_store_dwordx2 v[34:35], v[18:19], off offset:16
	global_store_dwordx2 v[34:35], v[20:21], off offset:32
	global_store_dwordx2 v[34:35], v[22:23], off offset:48
	global_store_dwordx2 v[34:35], v[0:1], off offset:64
	v_lshlrev_b32_e32 v0, 16, v51
	v_and_b32_e32 v1, 0xffff0000, v51
	v_pk_mul_f32 v[2:3], v[6:7], v[36:37] op_sel_hi:[1,0]
	v_pk_mul_f32 v[4:5], v[4:5], v[62:63]
	v_pk_mul_f32 v[0:1], v[2:3], v[0:1]
	v_cvt_pk_bf16_f32 v2, v4, v5
	v_cvt_pk_bf16_f32 v3, v0, v1
	global_store_dwordx2 v[34:35], v[2:3], off offset:80
	s_waitcnt vmcnt(7)
	v_lshlrev_b32_e32 v0, 16, v48
	v_and_b32_e32 v1, 0xffff0000, v48
	v_pk_mul_f32 v[2:3], v[8:9], v[36:37] op_sel_hi:[1,0]
	v_pk_mul_f32 v[4:5], v[10:11], v[36:37] op_sel_hi:[1,0]
	v_pk_mul_f32 v[0:1], v[2:3], v[0:1]
	v_lshlrev_b32_e32 v2, 16, v49
	v_and_b32_e32 v3, 0xffff0000, v49
	v_pk_mul_f32 v[2:3], v[4:5], v[2:3]
	v_cvt_pk_bf16_f32 v0, v0, v1
	v_cvt_pk_bf16_f32 v1, v2, v3
	s_waitcnt vmcnt(6)
	v_and_b32_e32 v3, 0xffff0000, v32
	v_lshlrev_b32_e32 v2, 16, v32
	v_pk_mul_f32 v[4:5], v[12:13], v[36:37] op_sel_hi:[1,0]
	global_store_dwordx2 v[34:35], v[0:1], off offset:96
	v_lshlrev_b32_e32 v0, 16, v33
	v_pk_mul_f32 v[2:3], v[4:5], v[2:3]
	v_and_b32_e32 v1, 0xffff0000, v33
	v_pk_mul_f32 v[4:5], v[14:15], v[36:37] op_sel_hi:[1,0]
	v_cvt_pk_bf16_f32 v2, v2, v3
	v_pk_mul_f32 v[0:1], v[4:5], v[0:1]
	s_nop 0
	v_cvt_pk_bf16_f32 v3, v0, v1
	global_store_dwordx2 v[34:35], v[2:3], off offset:112

.LBB0_390:
	s_or_b64 exec, exec, s[8:9]
	v_add_u32_e32 v10, v5, v142
	v_ashrrev_i32_e32 v11, 31, v10
	v_and_b32_e32 v1, 7, v1
	v_lshlrev_b64 v[122:123], 10, v[10:11]
	v_lshl_add_u64 v[10:11], s[16:17], 0, v[122:123]
	v_lshlrev_b32_e32 v112, 7, v1
	v_lshl_add_u64 v[10:11], v[10:11], 0, v[112:113]
	v_mov_b32_e32 v119, v113
	v_lshl_add_u64 v[10:11], v[10:11], 0, v[118:119]
	v_ashrrev_i32_e32 v7, 31, v6
	global_load_dwordx4 v[64:67], v[10:11], off
	global_load_dwordx4 v[68:71], v[10:11], off offset:32
	global_load_dwordx4 v[72:75], v[10:11], off offset:64
	global_load_dwordx4 v[76:79], v[10:11], off offset:96
	v_lshlrev_b64 v[10:11], 19, v[6:7]
	v_lshl_or_b32 v6, v6, 3, v1
	v_lshl_add_u64 v[10:11], s[20:21], 0, v[10:11]
	v_ashrrev_i32_e32 v7, 31, v6
	v_ashrrev_i32_e32 v5, 31, v4
	v_lshl_add_u64 v[124:125], v[10:11], 0, v[112:113]
	v_lshlrev_b64 v[10:11], 16, v[6:7]
	v_lshlrev_b64 v[4:5], 10, v[4:5]
	v_lshl_add_u64 v[126:127], s[26:27], 0, v[10:11]
	v_lshl_add_u64 v[10:11], s[18:19], 0, v[4:5]
	v_mov_b32_e32 v3, v131
	v_lshl_add_u64 v[10:11], v[10:11], 0, v[112:113]
	v_lshlrev_b64 v[12:13], 15, v[6:7]
	v_lshl_add_u64 v[128:129], s[30:31], 0, v[12:13]
	v_lshlrev_b32_e32 v16, 4, v3
	v_cndmask_b32_e32 v11, v125, v11, vcc
	v_cndmask_b32_e32 v10, v124, v10, vcc
	v_and_b32_e32 v14, 0x70, v16
	v_mov_b32_e32 v15, v113
	v_cndmask_b32_e32 v13, v127, v129, vcc
	v_cndmask_b32_e32 v12, v126, v128, vcc
	v_lshl_add_u64 v[10:11], v[10:11], 0, v[14:15]
	v_and_b32_e32 v14, 48, v16
	v_lshl_add_u64 v[12:13], v[12:13], 0, v[14:15]
	v_ashrrev_i32_e32 v14, 3, v3
	v_ashrrev_i32_e32 v15, 31, v14
	v_lshlrev_b64 v[14:15], 10, v[14:15]
	v_lshl_add_u64 v[14:15], v[10:11], 0, v[14:15]
	global_load_dwordx4 v[80:83], v[14:15], off
	v_ashrrev_i32_e32 v14, 2, v3
	v_ashrrev_i32_e32 v15, 31, v14
	v_lshlrev_b64 v[14:15], v2, v[14:15]
	v_lshl_add_u64 v[14:15], v[14:15], 1, v[12:13]
	v_add_u32_e32 v16, 64, v3
	global_load_dwordx4 v[84:87], v[14:15], off
	v_ashrrev_i32_e32 v14, 3, v16
	v_ashrrev_i32_e32 v15, 31, v14
	v_lshlrev_b64 v[14:15], 10, v[14:15]
	v_lshl_add_u64 v[14:15], v[10:11], 0, v[14:15]
	global_load_dwordx4 v[88:91], v[14:15], off
	v_ashrrev_i32_e32 v14, 2, v16
	v_ashrrev_i32_e32 v15, 31, v14
	v_lshlrev_b64 v[14:15], v2, v[14:15]
	v_lshl_add_u64 v[14:15], v[14:15], 1, v[12:13]
	v_add_u32_e32 v16, 0x80, v3
	global_load_dwordx4 v[92:95], v[14:15], off
	v_ashrrev_i32_e32 v14, 3, v16
	v_ashrrev_i32_e32 v15, 31, v14
	v_lshlrev_b64 v[14:15], 10, v[14:15]
	v_lshl_add_u64 v[14:15], v[10:11], 0, v[14:15]
	global_load_dwordx4 v[96:99], v[14:15], off
	v_ashrrev_i32_e32 v14, 2, v16
	v_ashrrev_i32_e32 v15, 31, v14
	v_lshlrev_b64 v[14:15], v2, v[14:15]
	v_lshl_add_u64 v[14:15], v[14:15], 1, v[12:13]
	v_add_u32_e32 v3, 0xc0, v3
	global_load_dwordx4 v[100:103], v[14:15], off
	v_ashrrev_i32_e32 v14, 3, v3
	v_ashrrev_i32_e32 v15, 31, v14
	v_lshlrev_b64 v[14:15], 10, v[14:15]
	v_lshl_add_u64 v[10:11], v[10:11], 0, v[14:15]
	global_load_dwordx4 v[104:107], v[10:11], off
	v_ashrrev_i32_e32 v10, 2, v3
	v_ashrrev_i32_e32 v11, 31, v10
	v_lshlrev_b64 v[2:3], v2, v[10:11]
	v_lshl_add_u64 v[2:3], v[2:3], 1, v[12:13]
	global_load_dwordx4 v[108:111], v[2:3], off
	v_lshlrev_b32_e32 v130, 6, v1
	v_mul_u32_u24_e32 v1, 0x1d1, v1
	v_lshlrev_b32_e32 v2, 2, v1
	v_sub_u32_e64 v1, v8, 4 clamp
	v_min_u32_e32 v119, 56, v1
	v_ashrrev_i32_e32 v1, 31, v0
	v_lshlrev_b64 v[0:1], 10, v[0:1]
	v_lshl_add_u64 v[0:1], s[18:19], 0, v[0:1]
	v_lshl_add_u64 v[134:135], v[0:1], 0, v[112:113]
	v_lshlrev_b64 v[0:1], 19, v[6:7]
	v_or_b32_e32 v151, v9, v142
	v_lshl_add_u64 v[136:137], s[28:29], 0, v[0:1]
	v_sub_u32_e64 v0, v151, 8 clamp
	v_mov_b32_e32 v3, v113
	v_min_u32_e32 v153, 48, v0
	v_or_b32_e32 v4, v4, v112
	v_mov_b32_e32 v155, 0
	v_lshl_add_u64 v[132:133], s[14:15], 0, v[2:3]
	v_sub_u32_e32 v152, v119, v8
	v_add_u32_e32 v154, 16, v153
	v_lshl_add_u64 v[138:139], s[34:35], 0, v[4:5]
	v_mov_b32_e32 v156, 0xff800000
	s_mov_b32 s65, 0
	s_mov_b32 s63, 32
	s_mov_b64 s[40:41], 0
	s_xor_b64 s[42:43], vcc, -1
	v_mov_b32_e32 v0, 0
	v_mov_b32_e32 v1, v155
	v_mov_b32_e32 v2, v155
	v_mov_b32_e32 v3, v155
	v_mov_b32_e32 v4, v155
	v_mov_b32_e32 v5, v155
	v_mov_b32_e32 v6, v155
	v_mov_b32_e32 v7, v155
	v_mov_b32_e32 v8, v155
	v_mov_b32_e32 v9, v155
	v_mov_b32_e32 v10, v155
	v_mov_b32_e32 v11, v155
	v_mov_b32_e32 v12, v155
	v_mov_b32_e32 v13, v155
	v_mov_b32_e32 v14, v155
	v_mov_b32_e32 v15, v155
	v_mov_b32_e32 v16, 0
	v_mov_b32_e32 v17, v155
	v_mov_b32_e32 v18, v155
	v_mov_b32_e32 v19, v155
	v_mov_b32_e32 v20, v155
	v_mov_b32_e32 v21, v155
	v_mov_b32_e32 v22, v155
	v_mov_b32_e32 v23, v155
	v_mov_b32_e32 v24, v155
	v_mov_b32_e32 v25, v155
	v_mov_b32_e32 v26, v155
	v_mov_b32_e32 v27, v155
	v_mov_b32_e32 v28, v155
	v_mov_b32_e32 v29, v155
	v_mov_b32_e32 v30, v155
	v_mov_b32_e32 v31, v155
	v_lshlrev_b32_e32 v222, 4, v131
	v_and_b32_e32 v220, 0x70, v222
	v_and_b32_e32 v221, 48, v222
	v_lshrrev_b32_e32 v222, 3, v131
	v_mad_u32_u24 v220, v222, s48, v220
	v_add_u32_e32 v220, v143, v220
	v_lshrrev_b32_e32 v222, 2, v131
	v_mad_u32_u24 v221, v222, s61, v221
	v_add_u32_e32 v221, v143, v221
	v_xor_b32_e32 v223, 32, v149
	v_lshlrev_b32_e32 v223, 2, v223
	v_add_u32_e32 v224, 0x1000, v146
	v_add_u32_e32 v225, 0x1800, v146
	v_and_b32_e32 v226, 7, v131
	v_lshrrev_b32_e32 v227, 3, v131
	v_lshlrev_b32_e32 v226, 4, v226
	v_lshl_add_u32 v226, v227, 10, v226
	v_and_b32_e32 v227, 3, v131
	v_lshlrev_b32_e32 v227, 4, v227
	v_lshrrev_b32_e32 v228, 2, v131
	s_branch .LBB0_393
.LBB0_392:
	s_or_b64 exec, exec, s[44:45]
	s_nop 8
	v_max_f32_e32 v48, v33, v33
	v_max_f32_e32 v49, v32, v32
	v_max_f32_e32 v48, v49, v48
	v_max3_f32 v48, v48, v34, v35
	v_max3_f32 v48, v48, v36, v37
	v_max3_f32 v48, v48, v38, v39
	v_max3_f32 v48, v48, v40, v41
	v_max3_f32 v48, v48, v42, v43
	v_max3_f32 v48, v48, v44, v45
	v_max3_f32 v49, v48, v46, v47
	s_add_i32 s63, s63, 32
	ds_bpermute_b32 v50, v223, v49
	v_cmp_eq_u32_e32 vcc, s64, v150
	v_lshl_add_u64 v[138:139], v[138:139], 0, s[38:39]
	s_or_b64 s[40:41], vcc, s[40:41]
	s_mov_b32 s65, s64
	s_waitcnt lgkmcnt(0)
	v_max3_f32 v49, v156, v49, v50
	v_sub_f32_e32 v32, v32, v49
	v_exp_f32_e32 v50, v32
	v_sub_f32_e32 v32, v33, v49
	v_exp_f32_e32 v51, v32
	v_sub_f32_e32 v34, v34, v49
	v_exp_f32_e32 v52, v34
	v_sub_f32_e32 v34, v35, v49
	v_exp_f32_e32 v53, v34
	v_sub_f32_e32 v34, v36, v49
	v_add_f32_e32 v33, 0, v50
	v_exp_f32_e32 v54, v34
	v_sub_f32_e32 v34, v37, v49
	v_add_f32_e32 v33, v51, v33
	v_exp_f32_e32 v55, v34
	v_sub_f32_e32 v34, v38, v49
	v_add_f32_e32 v33, v52, v33
	v_exp_f32_e32 v56, v34
	v_sub_f32_e32 v34, v39, v49
	v_add_f32_e32 v33, v53, v33
	v_exp_f32_e32 v39, v34
	v_sub_f32_e32 v34, v40, v49
	v_add_f32_e32 v33, v54, v33
	v_exp_f32_e32 v57, v34
	v_sub_f32_e32 v34, v41, v49
	v_add_f32_e32 v33, v55, v33
	v_exp_f32_e32 v58, v34
	v_add_f32_e32 v33, v56, v33
	v_add_f32_e32 v33, v39, v33
	v_add_f32_e32 v33, v57, v33
	v_add_f32_e32 v59, v58, v33
	v_sub_f32_e32 v33, v42, v49
	v_exp_f32_e32 v60, v33
	v_sub_f32_e32 v33, v43, v49
	v_sub_f32_e32 v32, v156, v49
	v_exp_f32_e32 v61, v33
	v_sub_f32_e32 v33, v44, v49
	v_exp_f32_e32 v62, v33
	v_sub_f32_e32 v33, v45, v49
	v_exp_f32_e32 v44, v32
	v_sub_f32_e32 v32, v46, v49
	v_cvt_pk_bf16_f32 v36, v50, v51
	v_exp_f32_e32 v45, v33
	v_exp_f32_e32 v46, v32
	ds_read2_b64 v[32:35], v224 offset0:64 offset1:66
	ds_read2_b64 v[40:43], v225 offset0:128 offset1:130
	v_pk_mul_f32 v[30:31], v[30:31], v[44:45] op_sel_hi:[1,0]
	v_pk_mul_f32 v[28:29], v[28:29], v[44:45] op_sel_hi:[1,0]
	v_pk_mul_f32 v[26:27], v[26:27], v[44:45] op_sel_hi:[1,0]
	v_pk_mul_f32 v[24:25], v[24:25], v[44:45] op_sel_hi:[1,0]
	v_pk_mul_f32 v[22:23], v[22:23], v[44:45] op_sel_hi:[1,0]
	v_pk_mul_f32 v[20:21], v[20:21], v[44:45] op_sel_hi:[1,0]
	v_pk_mul_f32 v[18:19], v[18:19], v[44:45] op_sel_hi:[1,0]
	v_pk_mul_f32 v[16:17], v[16:17], v[44:45] op_sel_hi:[1,0]
	v_pk_mul_f32 v[14:15], v[14:15], v[44:45] op_sel_hi:[1,0]
	v_pk_mul_f32 v[12:13], v[12:13], v[44:45] op_sel_hi:[1,0]
	v_cvt_pk_bf16_f32 v37, v52, v53
	v_cvt_pk_bf16_f32 v38, v54, v55
	v_cvt_pk_bf16_f32 v39, v56, v39
	v_pk_mul_f32 v[10:11], v[10:11], v[44:45] op_sel_hi:[1,0]
	v_pk_mul_f32 v[8:9], v[8:9], v[44:45] op_sel_hi:[1,0]
	v_pk_mul_f32 v[6:7], v[6:7], v[44:45] op_sel_hi:[1,0]
	v_pk_mul_f32 v[4:5], v[4:5], v[44:45] op_sel_hi:[1,0]
	v_pk_mul_f32 v[2:3], v[2:3], v[44:45] op_sel_hi:[1,0]
	v_pk_mul_f32 v[0:1], v[0:1], v[44:45] op_sel_hi:[1,0]
	s_waitcnt lgkmcnt(1)
	v_mfma_f32_32x32x16_bf16 v[16:31], v[32:35], v[36:39], v[16:31]
	ds_read2_b64 v[32:35], v224 offset0:68 offset1:70
	v_mov_b32_e32 v156, v49
	s_waitcnt lgkmcnt(1)
	v_mfma_f32_32x32x16_bf16 v[0:15], v[40:43], v[36:39], v[0:15]
	ds_read2_b64 v[40:43], v225 offset0:132 offset1:134
	v_sub_f32_e32 v36, v47, v49
	v_exp_f32_e32 v47, v36
	v_cvt_pk_bf16_f32 v36, v57, v58
	v_cvt_pk_bf16_f32 v37, v60, v61
	v_cvt_pk_bf16_f32 v38, v62, v45
	v_cvt_pk_bf16_f32 v39, v46, v47
	s_waitcnt lgkmcnt(1)
	s_nop 0
	v_mfma_f32_32x32x16_bf16 v[16:31], v[32:35], v[36:39], v[16:31]
	v_add_f32_e32 v32, v60, v59
	v_add_f32_e32 v32, v61, v32
	v_add_f32_e32 v32, v62, v32
	v_add_f32_e32 v32, v45, v32
	v_add_f32_e32 v32, v46, v32
	v_add_f32_e32 v32, v47, v32
	v_fmac_f32_e32 v32, v155, v44
	s_waitcnt lgkmcnt(0)
	v_mfma_f32_32x32x16_bf16 v[0:15], v[40:43], v[36:39], v[0:15]
	v_mov_b32_e32 v155, v32
	s_andn2_b64 exec, exec, s[40:41]
	s_cbranch_execz .LBB0_376
